# attention: global (in-order) loads/stores with counted vmcnt, ds ops for the queue word, static first two units per workgroup; gla_g2 scan: operands prefetched 3 blocks ahead, state stores deferred
# speedup vs baseline: 1.0040x; 1.0040x over previous
.LBB0_1109:
	s_andn2_saveexec_b64 s[0:1], s[4:5]
	s_cbranch_execz .LBB0_1112
	v_ashrrev_i32_e32 v2, 7, v4
	v_bfe_u32 v3, v4, 7, 6
	v_and_b32_e32 v4, 0xffffffc0, v2
	v_lshlrev_b32_e32 v2, 6, v2
	v_and_b32_e32 v0, 0x7f, v0
	v_and_b32_e32 v2, 0xfffff000, v2
	s_movk_i32 s8, 0x3c0
	v_ashrrev_i32_e32 v5, 31, v4
	v_or3_b32 v2, v2, v3, s8
	v_lshlrev_b64 v[4:5], 15, v[4:5]
	v_lshlrev_b32_e32 v3, 9, v3
	v_lshlrev_b32_e32 v0, 2, v0
	s_add_u32 s4, s6, 0x200000
	v_or3_b32 v4, v4, v3, v0
	s_addc_u32 s5, s7, 0
	s_add_u32 s10, s6, 0x25c00000
	s_addc_u32 s11, s7, 0
	s_add_u32 s100, s6, 0x26c00000
	s_addc_u32 s101, s7, 0
	v_add_u32_e32 v2, 0xfffffc40, v2
	v_lshlrev_b32_e32 v2, 2, v2
	v_mov_b32_e32 v164, v4
	v_add_u32_e32 v165, 0x8000, v4
	v_add_u32_e32 v166, 0x10000, v4
	v_add_u32_e32 v167, 0x18000, v4
	v_add_u32_e32 v168, 0x20000, v4
	v_add_u32_e32 v169, 0x28000, v4
	v_add_u32_e32 v170, 0x30000, v4
	v_add_u32_e32 v171, 0x38000, v4
	v_add_u32_e32 v172, 0x40000, v4
	v_add_u32_e32 v173, 0x48000, v4
	v_add_u32_e32 v174, 0x50000, v4
	v_add_u32_e32 v175, 0x58000, v4
	v_add_u32_e32 v176, 0x60000, v4
	v_add_u32_e32 v177, 0x68000, v4
	v_add_u32_e32 v190, 0x70000, v4
	v_add_u32_e32 v191, 0x78000, v4
	v_mov_b32_e32 v6, 0
	global_load_dword v100, v164, s[10:11]
	global_load_dword v7, v2, s[4:5]
	global_load_dword v101, v165, s[10:11]
	global_load_dword v8, v2, s[4:5] offset:256
	global_load_dword v102, v166, s[10:11]
	global_load_dword v9, v2, s[4:5] offset:512
	global_load_dword v103, v167, s[10:11]
	global_load_dword v10, v2, s[4:5] offset:768
	global_load_dword v104, v168, s[10:11]
	global_load_dword v11, v2, s[4:5] offset:1024
	global_load_dword v105, v169, s[10:11]
	global_load_dword v12, v2, s[4:5] offset:1280
	global_load_dword v106, v170, s[10:11]
	global_load_dword v13, v2, s[4:5] offset:1536
	global_load_dword v107, v171, s[10:11]
	global_load_dword v14, v2, s[4:5] offset:1792
	global_load_dword v108, v172, s[10:11]
	global_load_dword v15, v2, s[4:5] offset:2048
	global_load_dword v109, v173, s[10:11]
	global_load_dword v16, v2, s[4:5] offset:2304
	global_load_dword v110, v174, s[10:11]
	global_load_dword v17, v2, s[4:5] offset:2560
	global_load_dword v111, v175, s[10:11]
	global_load_dword v18, v2, s[4:5] offset:2816
	global_load_dword v112, v176, s[10:11]
	global_load_dword v19, v2, s[4:5] offset:3072
	global_load_dword v113, v177, s[10:11]
	global_load_dword v20, v2, s[4:5] offset:3328
	global_load_dword v114, v190, s[10:11]
	global_load_dword v21, v2, s[4:5] offset:3584
	global_load_dword v115, v191, s[10:11]
	global_load_dword v22, v2, s[4:5] offset:3840
	s_add_u32 s10, s10, 0x80000
	s_addc_u32 s11, s11, 0
	s_add_u32 s4, s4, 0x1000
	s_addc_u32 s5, s5, 0
	global_load_dword v116, v164, s[10:11]
	global_load_dword v23, v2, s[4:5]
	global_load_dword v117, v165, s[10:11]
	global_load_dword v24, v2, s[4:5] offset:256
	global_load_dword v118, v166, s[10:11]
	global_load_dword v25, v2, s[4:5] offset:512
	global_load_dword v119, v167, s[10:11]
	global_load_dword v26, v2, s[4:5] offset:768
	global_load_dword v120, v168, s[10:11]
	global_load_dword v27, v2, s[4:5] offset:1024
	global_load_dword v121, v169, s[10:11]
	global_load_dword v28, v2, s[4:5] offset:1280
	global_load_dword v122, v170, s[10:11]
	global_load_dword v29, v2, s[4:5] offset:1536
	global_load_dword v123, v171, s[10:11]
	global_load_dword v30, v2, s[4:5] offset:1792
	s_waitcnt vmcnt(32)
	global_load_dword v124, v172, s[10:11]
	global_load_dword v31, v2, s[4:5] offset:2048
	global_load_dword v125, v173, s[10:11]
	global_load_dword v32, v2, s[4:5] offset:2304
	global_load_dword v126, v174, s[10:11]
	global_load_dword v33, v2, s[4:5] offset:2560
	global_load_dword v127, v175, s[10:11]
	global_load_dword v34, v2, s[4:5] offset:2816
	global_load_dword v128, v176, s[10:11]
	global_load_dword v35, v2, s[4:5] offset:3072
	global_load_dword v129, v177, s[10:11]
	global_load_dword v36, v2, s[4:5] offset:3328
	global_load_dword v130, v190, s[10:11]
	global_load_dword v37, v2, s[4:5] offset:3584
	global_load_dword v131, v191, s[10:11]
	global_load_dword v38, v2, s[4:5] offset:3840
	v_mul_f32_e32 v7, 0x3fb8aa3b, v7
	v_mul_f32_e32 v8, 0x3fb8aa3b, v8
	v_mul_f32_e32 v9, 0x3fb8aa3b, v9
	v_mul_f32_e32 v10, 0x3fb8aa3b, v10
	v_mul_f32_e32 v11, 0x3fb8aa3b, v11
	v_mul_f32_e32 v12, 0x3fb8aa3b, v12
	v_mul_f32_e32 v13, 0x3fb8aa3b, v13
	v_mul_f32_e32 v14, 0x3fb8aa3b, v14
	v_exp_f32_e32 v7, v7
	v_exp_f32_e32 v8, v8
	v_exp_f32_e32 v9, v9
	v_exp_f32_e32 v10, v10
	v_exp_f32_e32 v11, v11
	v_exp_f32_e32 v12, v12
	v_exp_f32_e32 v13, v13
	v_exp_f32_e32 v14, v14
	v_fmac_f32_e32 v100, v6, v7
	v_fmac_f32_e32 v101, v100, v8
	v_fmac_f32_e32 v102, v101, v9
	v_fmac_f32_e32 v103, v102, v10
	v_fmac_f32_e32 v104, v103, v11
	v_fmac_f32_e32 v105, v104, v12
	v_fmac_f32_e32 v106, v105, v13
	v_fmac_f32_e32 v107, v106, v14
	s_waitcnt vmcnt(32)
	s_add_u32 s10, s10, 0x80000
	s_addc_u32 s11, s11, 0
	s_add_u32 s4, s4, 0x1000
	s_addc_u32 s5, s5, 0
	global_load_dword v132, v164, s[10:11]
	global_load_dword v7, v2, s[4:5]
	global_load_dword v133, v165, s[10:11]
	global_load_dword v8, v2, s[4:5] offset:256
	global_load_dword v134, v166, s[10:11]
	global_load_dword v9, v2, s[4:5] offset:512
	global_load_dword v135, v167, s[10:11]
	global_load_dword v10, v2, s[4:5] offset:768
	global_load_dword v136, v168, s[10:11]
	global_load_dword v11, v2, s[4:5] offset:1024
	global_load_dword v137, v169, s[10:11]
	global_load_dword v12, v2, s[4:5] offset:1280
	global_load_dword v138, v170, s[10:11]
	global_load_dword v13, v2, s[4:5] offset:1536
	global_load_dword v139, v171, s[10:11]
	global_load_dword v14, v2, s[4:5] offset:1792
	v_mul_f32_e32 v15, 0x3fb8aa3b, v15
	v_mul_f32_e32 v16, 0x3fb8aa3b, v16
	v_mul_f32_e32 v17, 0x3fb8aa3b, v17
	v_mul_f32_e32 v18, 0x3fb8aa3b, v18
	v_mul_f32_e32 v19, 0x3fb8aa3b, v19
	v_mul_f32_e32 v20, 0x3fb8aa3b, v20
	v_mul_f32_e32 v21, 0x3fb8aa3b, v21
	v_mul_f32_e32 v22, 0x3fb8aa3b, v22
	v_exp_f32_e32 v15, v15
	v_exp_f32_e32 v16, v16
	v_exp_f32_e32 v17, v17
	v_exp_f32_e32 v18, v18
	v_exp_f32_e32 v19, v19
	v_exp_f32_e32 v20, v20
	v_exp_f32_e32 v21, v21
	v_exp_f32_e32 v22, v22
	v_fmac_f32_e32 v108, v107, v15
	v_fmac_f32_e32 v109, v108, v16
	v_fmac_f32_e32 v110, v109, v17
	v_fmac_f32_e32 v111, v110, v18
	v_fmac_f32_e32 v112, v111, v19
	v_fmac_f32_e32 v113, v112, v20
	v_fmac_f32_e32 v114, v113, v21
	v_fmac_f32_e32 v115, v114, v22
	s_waitcnt vmcnt(32)
	global_load_dword v140, v172, s[10:11]
	global_load_dword v15, v2, s[4:5] offset:2048
	global_load_dword v141, v173, s[10:11]
	global_load_dword v16, v2, s[4:5] offset:2304
	global_load_dword v142, v174, s[10:11]
	global_load_dword v17, v2, s[4:5] offset:2560
	global_load_dword v143, v175, s[10:11]
	global_load_dword v18, v2, s[4:5] offset:2816
	global_load_dword v144, v176, s[10:11]
	global_load_dword v19, v2, s[4:5] offset:3072
	global_load_dword v145, v177, s[10:11]
	global_load_dword v20, v2, s[4:5] offset:3328
	global_load_dword v146, v190, s[10:11]
	global_load_dword v21, v2, s[4:5] offset:3584
	global_load_dword v147, v191, s[10:11]
	global_load_dword v22, v2, s[4:5] offset:3840
	v_mul_f32_e32 v23, 0x3fb8aa3b, v23
	v_mul_f32_e32 v24, 0x3fb8aa3b, v24
	v_mul_f32_e32 v25, 0x3fb8aa3b, v25
	v_mul_f32_e32 v26, 0x3fb8aa3b, v26
	v_mul_f32_e32 v27, 0x3fb8aa3b, v27
	v_mul_f32_e32 v28, 0x3fb8aa3b, v28
	v_mul_f32_e32 v29, 0x3fb8aa3b, v29
	v_mul_f32_e32 v30, 0x3fb8aa3b, v30
	v_exp_f32_e32 v23, v23
	v_exp_f32_e32 v24, v24
	v_exp_f32_e32 v25, v25
	v_exp_f32_e32 v26, v26
	v_exp_f32_e32 v27, v27
	v_exp_f32_e32 v28, v28
	v_exp_f32_e32 v29, v29
	v_exp_f32_e32 v30, v30
	v_fmac_f32_e32 v116, v115, v23
	v_fmac_f32_e32 v117, v116, v24
	v_fmac_f32_e32 v118, v117, v25
	v_fmac_f32_e32 v119, v118, v26
	v_fmac_f32_e32 v120, v119, v27
	v_fmac_f32_e32 v121, v120, v28
	v_fmac_f32_e32 v122, v121, v29
	v_fmac_f32_e32 v123, v122, v30
	s_waitcnt vmcnt(32)
	s_add_u32 s10, s10, 0x80000
	s_addc_u32 s11, s11, 0
	s_add_u32 s4, s4, 0x1000
	s_addc_u32 s5, s5, 0
	global_load_dword v148, v164, s[10:11]
	global_load_dword v23, v2, s[4:5]
	global_load_dword v149, v165, s[10:11]
	global_load_dword v24, v2, s[4:5] offset:256
	global_load_dword v150, v166, s[10:11]
	global_load_dword v25, v2, s[4:5] offset:512
	global_load_dword v151, v167, s[10:11]
	global_load_dword v26, v2, s[4:5] offset:768
	global_load_dword v152, v168, s[10:11]
	global_load_dword v27, v2, s[4:5] offset:1024
	global_load_dword v153, v169, s[10:11]
	global_load_dword v28, v2, s[4:5] offset:1280
	global_load_dword v154, v170, s[10:11]
	global_load_dword v29, v2, s[4:5] offset:1536
	global_load_dword v155, v171, s[10:11]
	global_load_dword v30, v2, s[4:5] offset:1792
	v_mul_f32_e32 v31, 0x3fb8aa3b, v31
	v_mul_f32_e32 v32, 0x3fb8aa3b, v32
	v_mul_f32_e32 v33, 0x3fb8aa3b, v33
	v_mul_f32_e32 v34, 0x3fb8aa3b, v34
	v_mul_f32_e32 v35, 0x3fb8aa3b, v35
	v_mul_f32_e32 v36, 0x3fb8aa3b, v36
	v_mul_f32_e32 v37, 0x3fb8aa3b, v37
	v_mul_f32_e32 v38, 0x3fb8aa3b, v38
	v_exp_f32_e32 v31, v31
	v_exp_f32_e32 v32, v32
	v_exp_f32_e32 v33, v33
	v_exp_f32_e32 v34, v34
	v_exp_f32_e32 v35, v35
	v_exp_f32_e32 v36, v36
	v_exp_f32_e32 v37, v37
	v_exp_f32_e32 v38, v38
	v_fmac_f32_e32 v124, v123, v31
	v_fmac_f32_e32 v125, v124, v32
	v_fmac_f32_e32 v126, v125, v33
	v_fmac_f32_e32 v127, v126, v34
	v_fmac_f32_e32 v128, v127, v35
	v_fmac_f32_e32 v129, v128, v36
	v_fmac_f32_e32 v130, v129, v37
	v_fmac_f32_e32 v131, v130, v38
	s_waitcnt vmcnt(32)
	global_load_dword v156, v172, s[10:11]
	global_load_dword v31, v2, s[4:5] offset:2048
	global_load_dword v157, v173, s[10:11]
	global_load_dword v32, v2, s[4:5] offset:2304
	global_load_dword v158, v174, s[10:11]
	global_load_dword v33, v2, s[4:5] offset:2560
	global_load_dword v159, v175, s[10:11]
	global_load_dword v34, v2, s[4:5] offset:2816
	global_load_dword v160, v176, s[10:11]
	global_load_dword v35, v2, s[4:5] offset:3072
	global_load_dword v161, v177, s[10:11]
	global_load_dword v36, v2, s[4:5] offset:3328
	global_load_dword v162, v190, s[10:11]
	global_load_dword v37, v2, s[4:5] offset:3584
	global_load_dword v163, v191, s[10:11]
	global_load_dword v38, v2, s[4:5] offset:3840
	v_mul_f32_e32 v7, 0x3fb8aa3b, v7
	v_mul_f32_e32 v8, 0x3fb8aa3b, v8
	v_mul_f32_e32 v9, 0x3fb8aa3b, v9
	v_mul_f32_e32 v10, 0x3fb8aa3b, v10
	v_mul_f32_e32 v11, 0x3fb8aa3b, v11
	v_mul_f32_e32 v12, 0x3fb8aa3b, v12
	v_mul_f32_e32 v13, 0x3fb8aa3b, v13
	v_mul_f32_e32 v14, 0x3fb8aa3b, v14
	v_exp_f32_e32 v7, v7
	v_exp_f32_e32 v8, v8
	v_exp_f32_e32 v9, v9
	v_exp_f32_e32 v10, v10
	v_exp_f32_e32 v11, v11
	v_exp_f32_e32 v12, v12
	v_exp_f32_e32 v13, v13
	v_exp_f32_e32 v14, v14
	v_fmac_f32_e32 v132, v131, v7
	v_fmac_f32_e32 v133, v132, v8
	v_fmac_f32_e32 v134, v133, v9
	v_fmac_f32_e32 v135, v134, v10
	v_fmac_f32_e32 v136, v135, v11
	v_fmac_f32_e32 v137, v136, v12
	v_fmac_f32_e32 v138, v137, v13
	v_fmac_f32_e32 v139, v138, v14
	s_waitcnt vmcnt(32)
	v_mul_f32_e32 v15, 0x3fb8aa3b, v15
	v_mul_f32_e32 v16, 0x3fb8aa3b, v16
	v_mul_f32_e32 v17, 0x3fb8aa3b, v17
	v_mul_f32_e32 v18, 0x3fb8aa3b, v18
	v_mul_f32_e32 v19, 0x3fb8aa3b, v19
	v_mul_f32_e32 v20, 0x3fb8aa3b, v20
	v_mul_f32_e32 v21, 0x3fb8aa3b, v21
	v_mul_f32_e32 v22, 0x3fb8aa3b, v22
	v_exp_f32_e32 v15, v15
	v_exp_f32_e32 v16, v16
	v_exp_f32_e32 v17, v17
	v_exp_f32_e32 v18, v18
	v_exp_f32_e32 v19, v19
	v_exp_f32_e32 v20, v20
	v_exp_f32_e32 v21, v21
	v_exp_f32_e32 v22, v22
	v_fmac_f32_e32 v140, v139, v15
	v_fmac_f32_e32 v141, v140, v16
	v_fmac_f32_e32 v142, v141, v17
	v_fmac_f32_e32 v143, v142, v18
	v_fmac_f32_e32 v144, v143, v19
	v_fmac_f32_e32 v145, v144, v20
	v_fmac_f32_e32 v146, v145, v21
	v_fmac_f32_e32 v147, v146, v22
	s_waitcnt vmcnt(16)
	v_mul_f32_e32 v23, 0x3fb8aa3b, v23
	v_mul_f32_e32 v24, 0x3fb8aa3b, v24
	v_mul_f32_e32 v25, 0x3fb8aa3b, v25
	v_mul_f32_e32 v26, 0x3fb8aa3b, v26
	v_mul_f32_e32 v27, 0x3fb8aa3b, v27
	v_mul_f32_e32 v28, 0x3fb8aa3b, v28
	v_mul_f32_e32 v29, 0x3fb8aa3b, v29
	v_mul_f32_e32 v30, 0x3fb8aa3b, v30
	v_exp_f32_e32 v23, v23
	v_exp_f32_e32 v24, v24
	v_exp_f32_e32 v25, v25
	v_exp_f32_e32 v26, v26
	v_exp_f32_e32 v27, v27
	v_exp_f32_e32 v28, v28
	v_exp_f32_e32 v29, v29
	v_exp_f32_e32 v30, v30
	v_fmac_f32_e32 v148, v147, v23
	v_fmac_f32_e32 v149, v148, v24
	v_fmac_f32_e32 v150, v149, v25
	v_fmac_f32_e32 v151, v150, v26
	v_fmac_f32_e32 v152, v151, v27
	v_fmac_f32_e32 v153, v152, v28
	v_fmac_f32_e32 v154, v153, v29
	v_fmac_f32_e32 v155, v154, v30
	s_waitcnt vmcnt(0)
	v_mul_f32_e32 v31, 0x3fb8aa3b, v31
	v_mul_f32_e32 v32, 0x3fb8aa3b, v32
	v_mul_f32_e32 v33, 0x3fb8aa3b, v33
	v_mul_f32_e32 v34, 0x3fb8aa3b, v34
	v_mul_f32_e32 v35, 0x3fb8aa3b, v35
	v_mul_f32_e32 v36, 0x3fb8aa3b, v36
	v_mul_f32_e32 v37, 0x3fb8aa3b, v37
	v_mul_f32_e32 v38, 0x3fb8aa3b, v38
	v_exp_f32_e32 v31, v31
	v_exp_f32_e32 v32, v32
	v_exp_f32_e32 v33, v33
	v_exp_f32_e32 v34, v34
	v_exp_f32_e32 v35, v35
	v_exp_f32_e32 v36, v36
	v_exp_f32_e32 v37, v37
	v_exp_f32_e32 v38, v38
	v_fmac_f32_e32 v156, v155, v31
	v_fmac_f32_e32 v157, v156, v32
	v_fmac_f32_e32 v158, v157, v33
	v_fmac_f32_e32 v159, v158, v34
	v_fmac_f32_e32 v160, v159, v35
	v_fmac_f32_e32 v161, v160, v36
	v_fmac_f32_e32 v162, v161, v37
	v_fmac_f32_e32 v163, v162, v38
	global_store_dword v164, v6, s[100:101]
	global_store_dword v165, v100, s[100:101]
	global_store_dword v166, v101, s[100:101]
	global_store_dword v167, v102, s[100:101]
	global_store_dword v168, v103, s[100:101]
	global_store_dword v169, v104, s[100:101]
	global_store_dword v170, v105, s[100:101]
	global_store_dword v171, v106, s[100:101]
	global_store_dword v172, v107, s[100:101]
	global_store_dword v173, v108, s[100:101]
	global_store_dword v174, v109, s[100:101]
	global_store_dword v175, v110, s[100:101]
	global_store_dword v176, v111, s[100:101]
	global_store_dword v177, v112, s[100:101]
	global_store_dword v190, v113, s[100:101]
	global_store_dword v191, v114, s[100:101]
	s_add_u32 s100, s100, 0x80000
	s_addc_u32 s101, s101, 0
	global_store_dword v164, v115, s[100:101]
	global_store_dword v165, v116, s[100:101]
	global_store_dword v166, v117, s[100:101]
	global_store_dword v167, v118, s[100:101]
	global_store_dword v168, v119, s[100:101]
	global_store_dword v169, v120, s[100:101]
	global_store_dword v170, v121, s[100:101]
	global_store_dword v171, v122, s[100:101]
	global_store_dword v172, v123, s[100:101]
	global_store_dword v173, v124, s[100:101]
	global_store_dword v174, v125, s[100:101]
	global_store_dword v175, v126, s[100:101]
	global_store_dword v176, v127, s[100:101]
	global_store_dword v177, v128, s[100:101]
	global_store_dword v190, v129, s[100:101]
	global_store_dword v191, v130, s[100:101]
	s_add_u32 s100, s100, 0x80000
	s_addc_u32 s101, s101, 0
	s_waitcnt vmcnt(32)
	global_store_dword v164, v131, s[100:101]
	global_store_dword v165, v132, s[100:101]
	global_store_dword v166, v133, s[100:101]
	global_store_dword v167, v134, s[100:101]
	global_store_dword v168, v135, s[100:101]
	global_store_dword v169, v136, s[100:101]
	global_store_dword v170, v137, s[100:101]
	global_store_dword v171, v138, s[100:101]
	global_store_dword v172, v139, s[100:101]
	global_store_dword v173, v140, s[100:101]
	global_store_dword v174, v141, s[100:101]
	global_store_dword v175, v142, s[100:101]
	global_store_dword v176, v143, s[100:101]
	global_store_dword v177, v144, s[100:101]
	global_store_dword v190, v145, s[100:101]
	global_store_dword v191, v146, s[100:101]
	s_add_u32 s100, s100, 0x80000
	s_addc_u32 s101, s101, 0
	s_waitcnt vmcnt(32)
	global_store_dword v164, v147, s[100:101]
	global_store_dword v165, v148, s[100:101]
	global_store_dword v166, v149, s[100:101]
	global_store_dword v167, v150, s[100:101]
	global_store_dword v168, v151, s[100:101]
	global_store_dword v169, v152, s[100:101]
	global_store_dword v170, v153, s[100:101]
	global_store_dword v171, v154, s[100:101]
	global_store_dword v172, v155, s[100:101]
	global_store_dword v173, v156, s[100:101]
	global_store_dword v174, v157, s[100:101]
	global_store_dword v175, v158, s[100:101]
	global_store_dword v176, v159, s[100:101]
	global_store_dword v177, v160, s[100:101]
	global_store_dword v190, v161, s[100:101]
	global_store_dword v191, v162, s[100:101]
.LBB0_1112:
	s_or_b64 exec, exec, s[0:1]
	v_readlane_b32 s40, v255, 0
	v_readlane_b32 s42, v255, 2
	v_readlane_b32 s43, v255, 3
	v_readlane_b32 s44, v255, 4
	v_readlane_b32 s45, v255, 5
	v_mov_b32_e32 v46, v222
	s_mov_b64 s[0:1], s[44:45]
	s_mov_b64 s[4:5], s[42:43]
	s_lshl_b32 s90, s80, 3
	s_lshl_b64 s[4:5], s[90:91], 2
	s_add_u32 s4, s0, s4
	s_addc_u32 s5, s1, s5
	v_readlane_b32 s41, v255, 1
	s_add_u32 s4, s4, 0x80000
	v_readfirstlane_b32 s8, v46
	s_addc_u32 s5, s5, 0
	v_cmp_eq_u32_e64 s[40:41], 0, v46
	v_readlane_b32 s46, v255, 6
	v_readlane_b32 s47, v255, 7
	s_and_saveexec_b64 s[6:7], s[40:41]
	s_cbranch_execz .LBB0_1114
	v_readlane_b32 s10, v252, 32
	s_nop 1
	s_lshr_b32 s10, s10, 3
	v_mov_b32_e32 v0, s10
	v_mov_b32_e32 v2, 0x23000
	v_add_u32_e32 v3, 0x100, v0
	ds_write_b32 v2, v0
	ds_write_b32 v2, v3 offset:4
	s_waitcnt lgkmcnt(0)
.LBB0_1114:
	s_or_b64 exec, exec, s[6:7]
	s_add_i32 s6, 0, 0x23000
	s_cmp_lg_u32 s6, -1
	v_readlane_b32 s10, v252, 37
	s_cselect_b32 s6, s6, 0
	v_readlane_b32 s11, v252, 38
	s_cselect_b32 s7, s11, 0
	v_mov_b32_e32 v2, s6
	s_add_i32 s6, 0, 0x23004
	s_cmp_lg_u32 s6, -1
	v_mov_b32_e32 v3, s7
	s_cselect_b32 s6, s6, 0
	s_cselect_b32 s7, s11, 0
	s_waitcnt lgkmcnt(0)
	s_barrier
	ds_read_b32 v99, v2
	v_mov_b32_e32 v2, s6
	v_mov_b32_e32 v3, s7
	ds_read_b32 v52, v2
	s_movk_i32 s6, 0x800
	s_waitcnt lgkmcnt(0)
	v_cmp_gt_i32_e32 vcc, s6, v99
	s_and_saveexec_b64 s[6:7], vcc
	s_cbranch_execz .LBB0_1141
	v_ashrrev_i32_e32 v3, 9, v99
	v_cmp_eq_u32_e32 vcc, 2, v3
	v_ashrrev_i32_e32 v47, 1, v46
	v_and_b32_e32 v2, 31, v99
	v_cndmask_b32_e64 v4, 0, 4, vcc
	v_cmp_ne_u32_e32 vcc, 1, v3
	v_add_u32_e32 v93, 0xffffff80, v47
	v_bfe_u32 v0, v99, 8, 1
	v_cndmask_b32_e32 v36, 2, v4, vcc
	v_lshrrev_b32_e64 v4, v36, 32
	v_add_u32_e32 v4, -1, v4
	v_bitop3_b32 v4, v4, v99, 31 bitop3:0x80
	v_sub_u32_e32 v5, 5, v36
	v_lshlrev_b32_e32 v37, 7, v4
	v_lshrrev_b32_e32 v2, v5, v2
	s_add_u32 s38, s0, 0x2b600000
	v_cmp_gt_i32_e32 vcc, 3, v3
	v_add_u32_e32 v40, v37, v93
	v_lshlrev_b32_e32 v3, 5, v46
	s_addc_u32 s39, s1, 0
	v_cmp_gt_i32_e64 s[42:43], 0, v40
	v_lshl_or_b32 v38, v0, 12, v2
	v_and_b32_e32 v44, 32, v3
	s_and_saveexec_b64 s[10:11], s[42:43]
	s_xor_b64 s[42:43], exec, s[10:11]
	v_lshl_or_b32 v38, v0, 12, v2
	v_and_b32_e32 v0, 32, v3
	v_mov_b32_e32 v48, v0
	v_mov_b64_e32 v[44:45], v[0:1]
	s_or_saveexec_b64 s[42:43], s[42:43]
	v_lshlrev_b32_e32 v0, 1, v99
	v_mov_b32_e32 v2, v1
	v_mov_b32_e32 v3, v1
	v_mov_b32_e32 v6, v1
	v_mov_b32_e32 v7, v1
	v_and_b32_e32 v39, 0x1c0, v0
	v_mov_b32_e32 v0, v1
	v_mov_b32_e32 v4, v1
	v_mov_b32_e32 v5, v1
	v_mov_b64_e32 v[22:23], v[6:7]
	v_mov_b64_e32 v[14:15], v[6:7]
	v_mov_b64_e32 v[10:11], v[6:7]
	v_mov_b64_e32 v[34:35], v[2:3]
	v_mov_b64_e32 v[30:31], v[2:3]
	v_mov_b64_e32 v[18:19], v[2:3]
	v_mov_b64_e32 v[26:27], v[2:3]
	v_mov_b64_e32 v[20:21], v[4:5]
	v_mov_b64_e32 v[12:13], v[4:5]
	v_mov_b64_e32 v[8:9], v[4:5]
	v_mov_b64_e32 v[32:33], v[0:1]
	v_mov_b64_e32 v[28:29], v[0:1]
	v_mov_b64_e32 v[16:17], v[0:1]
	v_mov_b64_e32 v[24:25], v[0:1]
	s_xor_b64 exec, exec, s[42:43]
	s_cbranch_execz .LBB0_1119
	v_lshrrev_b32_e32 v0, 5, v99
	v_lshlrev_b32_e32 v0, 4, v0
	v_and_b32_e32 v0, 64, v0
	v_or_b32_e32 v2, 0x400, v39
	v_or_b32_e32 v3, 0x880, v0
	v_cndmask_b32_e32 v6, v3, v2, vcc
	v_or_b32_e32 v2, 0x200, v39
	v_or_b32_e32 v0, 0x800, v0
	v_cndmask_b32_e32 v0, v0, v2, vcc
	v_lshl_add_u32 v4, v40, v36, v38
	v_mov_b64_e32 v[2:3], s[38:39]
	s_movk_i32 s10, 0x1200
	v_mad_u64_u32 v[2:3], s[10:11], v4, s10, v[2:3]
	v_lshlrev_b32_e32 v0, 1, v0
	v_lshl_add_u64 v[4:5], v[2:3], 0, v[0:1]
	v_lshlrev_b32_e32 v0, 1, v44
	v_lshlrev_b32_e32 v6, 1, v6
	v_mov_b32_e32 v7, v1
	v_lshl_add_u64 v[4:5], v[4:5], 0, v[0:1]
	v_lshl_add_u64 v[2:3], v[2:3], 0, v[6:7]
	v_lshl_add_u64 v[2:3], v[2:3], 0, v[0:1]
	flat_load_dwordx4 v[24:27], v[4:5]
	flat_load_dwordx4 v[16:19], v[4:5] offset:16
	flat_load_dwordx4 v[8:11], v[2:3]
	flat_load_dwordx4 v[12:15], v[2:3] offset:16
	flat_load_dwordx4 v[28:31], v[4:5] offset:32
	flat_load_dwordx4 v[32:35], v[4:5] offset:48
	flat_load_dwordx4 v[20:23], v[2:3] offset:32
	s_nop 0
	flat_load_dwordx4 v[4:7], v[2:3] offset:48
	v_mov_b32_e32 v45, v1
	v_mov_b32_e32 v48, v44

.LBB0_1120:
	s_or_b64 exec, exec, s[46:47]
	s_lshl_b32 s11, s11, 2
	s_add_i32 s11, s11, 0
	v_readlane_b32 s26, v252, 37
	s_add_i32 s11, s11, 0x23000
	v_readlane_b32 s27, v252, 38
	v_mov_b32_e32 v2, s11
	s_waitcnt lgkmcnt(0)
	v_mov_b32_e32 v3, s27
	s_and_saveexec_b64 s[100:101], s[40:41]
	s_cbranch_execz .Lattnq_skip
	s_waitcnt vmcnt(4)
	v_add_u32_e32 v240, 0x200, v240
	ds_write_b32 v2, v240
	s_waitcnt lgkmcnt(0)
.Lattnq_skip:
	s_or_b64 exec, exec, s[100:101]
	s_barrier
	ds_read_b32 v52, v2
	s_movk_i32 s11, 0x7ff
	v_cmp_lt_i32_e32 vcc, s11, v199
	s_or_b64 s[56:57], vcc, s[56:57]
	s_mov_b32 s11, s10
	v_mov_b32_e32 v99, v199
	s_andn2_b64 exec, exec, s[56:57]
	s_cbranch_execz .LBB0_1141

.LBB0_1123:
	s_or_b64 exec, exec, s[44:45]
	s_movk_i32 s10, 0x800
	v_cmp_gt_i32_e64 s[44:45], s10, v199
	s_and_saveexec_b64 s[58:59], s[44:45]
	s_cbranch_execz .LBB0_1129
	v_ashrrev_i32_e32 v3, 9, v199
	v_cmp_eq_u32_e32 vcc, 2, v3
	v_and_b32_e32 v2, 31, v199
	v_bfe_u32 v0, v199, 8, 1
	v_cndmask_b32_e64 v4, 0, 4, vcc
	v_cmp_ne_u32_e32 vcc, 1, v3
	s_nop 1
	v_cndmask_b32_e32 v36, 2, v4, vcc
	v_lshrrev_b32_e64 v4, v36, 32
	v_add_u32_e32 v4, -1, v4
	v_bitop3_b32 v4, v4, v199, 31 bitop3:0x80
	v_sub_u32_e32 v5, 5, v36
	v_lshlrev_b32_e32 v37, 7, v4
	v_lshrrev_b32_e32 v2, v5, v2
	v_add_u32_e32 v40, v37, v93
	v_cmp_gt_i32_e32 vcc, 3, v3
	v_cmp_gt_i32_e64 s[46:47], 0, v40
	v_lshl_or_b32 v38, v0, 12, v2
	s_and_saveexec_b64 s[34:35], s[46:47]
	s_xor_b64 s[46:47], exec, s[34:35]
	v_lshl_or_b32 v38, v0, 12, v2
	s_or_saveexec_b64 s[46:47], s[46:47]
	v_lshlrev_b32_e32 v0, 1, v199
	v_mov_b32_e32 v2, v1
	v_mov_b32_e32 v3, v1
	v_mov_b32_e32 v6, v1
	v_mov_b32_e32 v7, v1
	v_and_b32_e32 v39, 0x1c0, v0
	v_mov_b32_e32 v0, v1
	v_mov_b32_e32 v4, v1
	v_mov_b32_e32 v5, v1
	v_mov_b64_e32 v[22:23], v[6:7]
	v_mov_b64_e32 v[14:15], v[6:7]
	v_mov_b64_e32 v[10:11], v[6:7]
	v_mov_b64_e32 v[34:35], v[2:3]
	v_mov_b64_e32 v[30:31], v[2:3]
	v_mov_b64_e32 v[18:19], v[2:3]
	v_mov_b64_e32 v[26:27], v[2:3]
	v_mov_b64_e32 v[20:21], v[4:5]
	v_mov_b64_e32 v[12:13], v[4:5]
	v_mov_b64_e32 v[8:9], v[4:5]
	v_mov_b64_e32 v[32:33], v[0:1]
	v_mov_b64_e32 v[28:29], v[0:1]
	v_mov_b64_e32 v[16:17], v[0:1]
	v_mov_b64_e32 v[24:25], v[0:1]
	s_xor_b64 exec, exec, s[46:47]
	s_cbranch_execz .LBB0_1128
	v_lshrrev_b32_e32 v0, 5, v199
	v_lshlrev_b32_e32 v0, 4, v0
	v_and_b32_e32 v0, 64, v0
	v_or_b32_e32 v2, 0x400, v39
	v_or_b32_e32 v3, 0x880, v0
	v_cndmask_b32_e32 v6, v3, v2, vcc
	v_or_b32_e32 v2, 0x200, v39
	v_or_b32_e32 v0, 0x800, v0
	v_cndmask_b32_e32 v0, v0, v2, vcc
	v_lshl_add_u32 v4, v40, v36, v38
	v_mov_b64_e32 v[2:3], s[38:39]
	s_movk_i32 s10, 0x1200
	v_mad_u64_u32 v[2:3], s[34:35], v4, s10, v[2:3]
	v_lshlrev_b32_e32 v0, 1, v0
	v_lshl_add_u64 v[4:5], v[2:3], 0, v[0:1]
	v_lshlrev_b32_e32 v0, 1, v6
	v_lshl_add_u64 v[4:5], v[4:5], 0, v[94:95]
	v_lshl_add_u64 v[2:3], v[2:3], 0, v[0:1]
	v_lshl_add_u64 v[2:3], v[2:3], 0, v[94:95]
	global_load_dwordx4 v[24:27], v[4:5], off
	global_load_dwordx4 v[16:19], v[4:5], off offset:16
	global_load_dwordx4 v[8:11], v[2:3], off
	global_load_dwordx4 v[12:15], v[2:3], off offset:16
	global_load_dwordx4 v[28:31], v[4:5], off offset:32
	global_load_dwordx4 v[32:35], v[4:5], off offset:48
	global_load_dwordx4 v[20:23], v[2:3], off offset:32
	s_nop 0
	global_load_dwordx4 v[4:7], v[2:3], off offset:48
.LBB0_1128:
	s_or_b64 exec, exec, s[46:47]
	v_or_b32_e32 v0, 0x600, v39
	v_add_u32_e32 v2, v37, v103
	v_cndmask_b32_e32 v0, v0, v39, vcc
	v_lshl_add_u32 v36, v2, v36, v38
	v_mov_b64_e32 v[2:3], s[38:39]
	s_movk_i32 s10, 0x1200
	v_mad_i64_i32 v[2:3], s[34:35], v36, s10, v[2:3]
	v_lshlrev_b32_e32 v0, 1, v0
	v_lshl_add_u64 v[2:3], v[2:3], 0, v[0:1]
	v_mov_b32_e32 v97, v1
	v_lshl_add_u64 v[2:3], v[2:3], 0, v[96:97]
	global_load_dwordx4 v[36:39], v[2:3], off
	global_load_dwordx4 v[40:43], v[2:3], off offset:64

.Lattn_mask_join:
	v_xor_b32_e32 v52, 16, v226
	v_add_u32_e32 v53, 64, v53
	v_cmp_lt_i32_e32 vcc, v52, v53
	v_sub_u32_e32 v62, 5, v0
	s_lshl_b32 s10, s8, 1
	v_cndmask_b32_e32 v52, v226, v52, vcc
	v_lshlrev_b32_e32 v54, 2, v52
	ds_bpermute_b32 v52, v54, v2
	s_add_i32 s10, s10, s12
	v_add_u32_e32 v3, v3, v103
	s_waitcnt lgkmcnt(0)
	v_max_f32_e32 v52, v52, v52
	v_max_f32_e32 v2, v2, v52
	v_xor_b32_e32 v52, 32, v226
	v_cmp_lt_i32_e32 vcc, v52, v53
	v_and_b32_e32 v53, 31, v99
	v_lshrrev_b32_e32 v53, v62, v53
	v_cndmask_b32_e32 v52, v226, v52, vcc
	v_lshlrev_b32_e32 v52, 2, v52
	ds_bpermute_b32 v61, v52, v2
	v_cmp_ne_u32_e32 vcc, 3, v98
	s_waitcnt lgkmcnt(0)
	v_max_f32_e32 v61, v61, v61
	v_max_f32_e32 v2, v2, v61
	v_sub_f32_e32 v62, v72, v2
	v_sub_f32_e32 v72, v74, v2
	v_sub_f32_e32 v74, v88, v2
	v_mul_f32_e32 v74, 0x3fb8aa3b, v74
	v_exp_f32_e32 v88, v74
	v_sub_f32_e32 v74, v89, v2
	v_mul_f32_e32 v74, 0x3fb8aa3b, v74
	v_exp_f32_e32 v89, v74
	v_sub_f32_e32 v74, v90, v2
	v_mul_f32_e32 v74, 0x3fb8aa3b, v74
	v_exp_f32_e32 v90, v74
	v_sub_f32_e32 v74, v91, v2
	v_sub_f32_e32 v56, v56, v2
	v_mul_f32_e32 v74, 0x3fb8aa3b, v74
	v_mul_f32_e32 v56, 0x3fb8aa3b, v56
	v_sub_f32_e32 v57, v57, v2
	v_exp_f32_e32 v91, v74
	v_sub_f32_e32 v74, v84, v2
	v_exp_f32_e32 v56, v56
	v_mul_f32_e32 v57, 0x3fb8aa3b, v57
	v_sub_f32_e32 v58, v58, v2
	v_mul_f32_e32 v74, 0x3fb8aa3b, v74
	v_exp_f32_e32 v57, v57
	v_mul_f32_e32 v58, 0x3fb8aa3b, v58
	v_sub_f32_e32 v59, v59, v2
	v_exp_f32_e32 v84, v74
	v_sub_f32_e32 v74, v85, v2
	v_exp_f32_e32 v58, v58
	v_mul_f32_e32 v59, 0x3fb8aa3b, v59
	v_mul_f32_e32 v74, 0x3fb8aa3b, v74
	v_exp_f32_e32 v59, v59
	v_mul_f32_e32 v62, 0x3fb8aa3b, v62
	v_sub_f32_e32 v63, v73, v2
	v_exp_f32_e32 v85, v74
	v_sub_f32_e32 v74, v86, v2
	v_add_f32_e32 v61, 0, v56
	v_exp_f32_e32 v62, v62
	v_mul_f32_e32 v63, 0x3fb8aa3b, v63
	v_mul_f32_e32 v74, 0x3fb8aa3b, v74
	v_add_f32_e32 v61, v57, v61
	v_exp_f32_e32 v63, v63
	v_mul_f32_e32 v72, 0x3fb8aa3b, v72
	v_sub_f32_e32 v73, v75, v2
	v_exp_f32_e32 v86, v74
	v_sub_f32_e32 v74, v87, v2
	v_add_f32_e32 v61, v58, v61
	v_exp_f32_e32 v72, v72
	v_mul_f32_e32 v73, 0x3fb8aa3b, v73
	v_mul_f32_e32 v74, 0x3fb8aa3b, v74
	v_add_f32_e32 v61, v59, v61
	v_exp_f32_e32 v73, v73
	v_exp_f32_e32 v87, v74
	v_sub_f32_e32 v74, v80, v2
	v_add_f32_e32 v61, v62, v61
	v_mul_f32_e32 v74, 0x3fb8aa3b, v74
	v_add_f32_e32 v61, v63, v61
	v_exp_f32_e32 v97, v74
	v_sub_f32_e32 v74, v81, v2
	v_add_f32_e32 v61, v72, v61
	v_mul_f32_e32 v74, 0x3fb8aa3b, v74
	v_add_f32_e32 v61, v73, v61
	v_exp_f32_e32 v206, v74
	v_sub_f32_e32 v74, v82, v2
	v_add_f32_e32 v61, v88, v61
	v_mul_f32_e32 v74, 0x3fb8aa3b, v74
	v_add_f32_e32 v61, v89, v61
	v_exp_f32_e32 v207, v74
	v_sub_f32_e32 v74, v83, v2
	v_add_f32_e32 v61, v90, v61
	v_mul_f32_e32 v74, 0x3fb8aa3b, v74
	v_add_f32_e32 v61, v91, v61
	v_exp_f32_e32 v208, v74
	v_sub_f32_e32 v74, v76, v2
	v_add_f32_e32 v61, v84, v61
	v_mul_f32_e32 v74, 0x3fb8aa3b, v74
	v_sub_f32_e32 v64, v64, v2
	v_add_f32_e32 v61, v85, v61
	v_exp_f32_e32 v209, v74
	v_sub_f32_e32 v74, v77, v2
	v_mul_f32_e32 v64, 0x3fb8aa3b, v64
	v_add_f32_e32 v61, v86, v61
	v_mul_f32_e32 v74, 0x3fb8aa3b, v74
	v_exp_f32_e32 v213, v64
	v_sub_f32_e32 v64, v65, v2
	v_add_f32_e32 v61, v87, v61
	v_exp_f32_e32 v210, v74
	v_sub_f32_e32 v74, v78, v2
	v_mul_f32_e32 v64, 0x3fb8aa3b, v64
	v_add_f32_e32 v61, v97, v61
	v_mul_f32_e32 v74, 0x3fb8aa3b, v74
	v_exp_f32_e32 v214, v64
	v_sub_f32_e32 v64, v66, v2
	v_add_f32_e32 v61, v206, v61
	v_exp_f32_e32 v211, v74
	v_sub_f32_e32 v74, v79, v2
	v_mul_f32_e32 v64, 0x3fb8aa3b, v64
	v_add_f32_e32 v61, v207, v61
	v_mul_f32_e32 v74, 0x3fb8aa3b, v74
	v_exp_f32_e32 v215, v64
	v_sub_f32_e32 v64, v67, v2
	v_add_f32_e32 v61, v208, v61
	v_exp_f32_e32 v212, v74
	v_mul_f32_e32 v64, 0x3fb8aa3b, v64
	v_add_f32_e32 v61, v209, v61
	v_exp_f32_e32 v216, v64
	v_sub_f32_e32 v64, v68, v2
	v_add_f32_e32 v61, v210, v61
	v_mul_f32_e32 v64, 0x3fb8aa3b, v64
	v_sub_f32_e32 v60, v60, v2
	v_add_f32_e32 v61, v211, v61
	v_exp_f32_e32 v217, v64
	v_sub_f32_e32 v64, v69, v2
	v_mul_f32_e32 v60, 0x3fb8aa3b, v60
	v_add_f32_e32 v61, v212, v61
	v_mul_f32_e32 v64, 0x3fb8aa3b, v64
	v_exp_f32_e32 v221, v60
	v_add_f32_e32 v61, v213, v61
	v_exp_f32_e32 v218, v64
	v_sub_f32_e32 v64, v70, v2
	v_add_f32_e32 v61, v214, v61
	v_mul_f32_e32 v64, 0x3fb8aa3b, v64
	v_add_f32_e32 v61, v215, v61
	v_exp_f32_e32 v219, v64
	v_cvt_pk_bf16_f32 v56, v56, v57
	v_add_f32_e32 v61, v216, v61
	v_add_f32_e32 v61, v217, v61
	v_cvt_pk_bf16_f32 v57, v58, v59
	v_add_f32_e32 v61, v218, v61
	v_lshl_add_u32 v74, v92, 1, s10
	v_and_b32_sdwa v64, v72, v225 dst_sel:DWORD dst_unused:UNUSED_PAD src0_sel:WORD_1 src1_sel:DWORD
	v_add_f32_e32 v76, v219, v61
	v_sub_f32_e32 v61, v71, v2
	v_cvt_pk_bf16_f32 v58, v62, v63
	v_and_b32_sdwa v59, v73, v225 dst_sel:DWORD dst_unused:UNUSED_PAD src0_sel:WORD_1 src1_sel:DWORD
	v_lshl_add_u32 v68, v197, 1, v74
	v_add3_u32 v69, v72, v64, s23
	v_lshl_add_u32 v72, v198, 1, v74
	v_mul_f32_e32 v61, 0x3fb8aa3b, v61
	v_add_u32_e32 v232, 0x9000, v68
	v_add_u32_e32 v233, 0xb000, v68
	v_add3_u32 v59, v73, v59, s23
	v_add_u32_e32 v234, 0xd000, v68
	v_add_u32_e32 v235, 0x9000, v72
	v_exp_f32_e32 v220, v61
	ds_read2_b64 v[60:63], v232 offset1:4
	ds_read2_b64 v[64:67], v233 offset0:32 offset1:36
	v_perm_b32 v59, v59, v69, s22
	ds_read2_b64 v[68:71], v234 offset0:64 offset1:68
	ds_read2_b64 v[72:75], v235 offset1:4
	v_add_f32_e32 v76, v220, v76
	v_add_f32_e32 v236, v221, v76
	v_sub_f32_e32 v76, v201, v2
	s_waitcnt lgkmcnt(0)
	v_mfma_f32_16x16x32_bf16 v[60:63], v[60:63], v[56:59], 0
	v_mul_f32_e32 v76, 0x3fb8aa3b, v76
	v_exp_f32_e32 v201, v76
	ds_read2_b64 v[76:79], v232 offset0:8 offset1:12
	v_mfma_f32_16x16x32_bf16 v[64:67], v[64:67], v[56:59], 0
	v_sub_f32_e32 v200, v200, v2
	ds_read2_b64 v[80:83], v233 offset0:40 offset1:44
	v_sub_f32_e32 v55, v55, v2
	v_mfma_f32_16x16x32_bf16 v[68:71], v[68:71], v[56:59], 0
	v_mul_f32_e32 v55, 0x3fb8aa3b, v55
	v_exp_f32_e32 v55, v55
	s_movk_i32 s10, 0x1000
	v_mfma_f32_16x16x32_bf16 v[56:59], v[72:75], v[56:59], 0
	v_cvt_pk_bf16_f32 v72, v88, v89
	v_cvt_pk_bf16_f32 v73, v90, v91
	v_cvt_pk_bf16_f32 v74, v84, v85
	v_cvt_pk_bf16_f32 v75, v86, v87
	ds_read2_b64 v[84:87], v234 offset0:72 offset1:76
	v_sub_f32_e32 v91, v203, v2
	s_waitcnt lgkmcnt(0)
	v_mfma_f32_16x16x32_bf16 v[60:63], v[76:79], v[72:75], v[60:63]
	v_mul_f32_e32 v76, 0x3fb8aa3b, v200
	v_exp_f32_e32 v88, v76
	ds_read2_b64 v[76:79], v235 offset0:8 offset1:12
	v_mfma_f32_16x16x32_bf16 v[64:67], v[80:83], v[72:75], v[64:67]
	v_add_f32_e32 v80, v201, v236
	v_add_f32_e32 v89, v88, v80
	v_sub_f32_e32 v80, v202, v2
	v_mfma_f32_16x16x32_bf16 v[68:71], v[84:87], v[72:75], v[68:71]
	v_mul_f32_e32 v80, 0x3fb8aa3b, v80
	s_waitcnt lgkmcnt(0)
	v_mfma_f32_16x16x32_bf16 v[56:59], v[76:79], v[72:75], v[56:59]
	ds_read2_b64 v[76:79], v232 offset0:16 offset1:20
	v_cvt_pk_bf16_f32 v72, v97, v206
	v_cvt_pk_bf16_f32 v73, v207, v208
	v_cvt_pk_bf16_f32 v74, v209, v210
	v_cvt_pk_bf16_f32 v75, v211, v212
	v_exp_f32_e32 v90, v80
	ds_read2_b64 v[80:83], v233 offset0:48 offset1:52
	s_waitcnt lgkmcnt(0)
	v_mfma_f32_16x16x32_bf16 v[60:63], v[76:79], v[72:75], v[60:63]
	v_mul_f32_e32 v76, 0x3fb8aa3b, v91
	ds_read2_b64 v[84:87], v234 offset0:80 offset1:84
	v_exp_f32_e32 v91, v76
	ds_read2_b64 v[76:79], v235 offset0:16 offset1:20
	v_mfma_f32_16x16x32_bf16 v[64:67], v[80:83], v[72:75], v[64:67]
	v_sub_f32_e32 v200, v205, v2
	v_add_f32_e32 v80, v90, v89
	v_add_f32_e32 v89, v91, v80
	s_waitcnt lgkmcnt(0)
	v_mfma_f32_16x16x32_bf16 v[68:71], v[84:87], v[72:75], v[68:71]
	v_sub_f32_e32 v80, v204, v2
	v_mfma_f32_16x16x32_bf16 v[56:59], v[76:79], v[72:75], v[56:59]
	ds_read2_b64 v[76:79], v232 offset0:24 offset1:28
	v_cvt_pk_bf16_f32 v72, v213, v214
	v_cvt_pk_bf16_f32 v73, v215, v216
	v_cvt_pk_bf16_f32 v74, v217, v218
	v_cvt_pk_bf16_f32 v75, v219, v220
	v_mul_f32_e32 v80, 0x3fb8aa3b, v80
	ds_read2_b64 v[84:87], v234 offset0:88 offset1:92
	s_waitcnt lgkmcnt(0)
	v_mfma_f32_16x16x32_bf16 v[60:63], v[76:79], v[72:75], v[60:63]
	v_mul_f32_e32 v76, 0x3fb8aa3b, v200
	v_exp_f32_e32 v200, v76
	ds_read2_b64 v[76:79], v235 offset0:24 offset1:28
	v_exp_f32_e32 v97, v80
	ds_read2_b64 v[80:83], v233 offset0:56 offset1:60
	s_waitcnt lgkmcnt(0)
	v_mfma_f32_16x16x32_bf16 v[76:79], v[76:79], v[72:75], v[56:59]
	s_nop 2
	v_mfma_f32_16x16x32_bf16 v[68:71], v[84:87], v[72:75], v[68:71]
	v_cvt_pk_bf16_f32 v84, v221, v201
	v_mfma_f32_16x16x32_bf16 v[80:83], v[80:83], v[72:75], v[64:67]
	v_cvt_pk_bf16_f32 v85, v88, v90
	v_add_f32_e32 v64, v97, v89
	v_add_f32_e32 v64, v200, v64
	v_add_f32_e32 v204, v55, v64
	ds_read2_b64 v[56:59], v232 offset0:32 offset1:36
	ds_read2_b64 v[72:75], v233 offset0:64 offset1:68
	v_cvt_pk_bf16_f32 v86, v91, v97
	v_and_b32_sdwa v65, v200, v225 dst_sel:DWORD dst_unused:UNUSED_PAD src0_sel:WORD_1 src1_sel:DWORD
	v_add3_u32 v65, v200, v65, s23
	ds_read2_b64 v[88:91], v234 offset0:96 offset1:100
	ds_read2_b64 v[200:203], v235 offset0:32 offset1:36
	ds_bpermute_b32 v54, v54, v204
	v_and_b32_sdwa v64, v55, v225 dst_sel:DWORD dst_unused:UNUSED_PAD src0_sel:WORD_1 src1_sel:DWORD
	v_add3_u32 v55, v55, v64, s23
	v_perm_b32 v87, v55, v65, s22
	v_lshlrev_b32_e32 v55, 4, v99
	v_and_or_b32 v53, v55, s10, v53
	s_waitcnt lgkmcnt(0)
	v_mfma_f32_16x16x32_bf16 v[64:67], v[56:59], v[84:87], v[60:63]
	v_mfma_f32_16x16x32_bf16 v[60:63], v[72:75], v[84:87], v[80:83]
	v_add_f32_e32 v73, v204, v54
	ds_bpermute_b32 v75, v52, v73
	v_lshl_add_u32 v72, v3, v0, v53
	v_mfma_f32_16x16x32_bf16 v[56:59], v[88:91], v[84:87], v[68:71]
	v_bfe_u32 v74, v99, 5, 3
	v_lshlrev_b32_e32 v0, 7, v74
	s_waitcnt lgkmcnt(0)
	v_add_f32_e32 v3, v73, v75
	v_mfma_f32_16x16x32_bf16 v[52:55], v[200:203], v[84:87], v[76:79]
	v_ashrrev_i32_e32 v73, 31, v72
	v_lshlrev_b32_e32 v70, 1, v92
	s_and_saveexec_b64 s[34:35], vcc
	s_xor_b64 s[46:47], exec, s[34:35]
	s_cbranch_execz .LBB0_1138
	v_ashrrev_i32_e32 v99, 31, v98
	v_lshlrev_b64 v[68:69], 13, v[98:99]
	v_lshl_add_u64 v[68:69], v[68:69], 0, v[72:73]
	v_lshlrev_b64 v[72:73], 10, v[68:69]
	v_lshl_add_u64 v[72:73], s[52:53], 0, v[72:73]
	v_lshl_add_u64 v[72:73], v[72:73], 0, v[0:1]
	v_bfe_u32 v0, v64, 16, 1
	v_add3_u32 v0, v64, v0, s23
	v_bfe_u32 v64, v65, 16, 1
	v_lshrrev_b32_e32 v0, 16, v0
	v_add3_u32 v64, v65, v64, s23
	v_and_or_b32 v64, v64, s15, v0
	v_cvt_pk_bf16_f32 v65, v66, v67
	v_bfe_u32 v0, v60, 16, 1
	v_add3_u32 v0, v60, v0, s23
	v_bfe_u32 v60, v61, 16, 1
	v_lshrrev_b32_e32 v0, 16, v0
	v_add3_u32 v60, v61, v60, s23
	v_and_or_b32 v60, v60, s15, v0
	v_cvt_pk_bf16_f32 v61, v62, v63
	v_bfe_u32 v0, v56, 16, 1
	v_add3_u32 v0, v56, v0, s23
	v_bfe_u32 v56, v57, 16, 1
	v_lshrrev_b32_e32 v0, 16, v0
	v_add3_u32 v56, v57, v56, s23
	v_and_or_b32 v56, v56, s15, v0
	v_cvt_pk_bf16_f32 v57, v58, v59
	v_bfe_u32 v0, v52, 16, 1
	v_add3_u32 v0, v52, v0, s23
	v_bfe_u32 v52, v53, 16, 1
	v_lshrrev_b32_e32 v0, 16, v0
	v_add3_u32 v52, v53, v52, s23
	v_and_or_b32 v52, v52, s15, v0
	v_mov_b32_e32 v71, v1
	v_lshl_add_u64 v[70:71], v[72:73], 0, v[70:71]
	v_cvt_pk_bf16_f32 v53, v54, v55
	global_store_dwordx2 v[70:71], v[64:65], off nt
	global_store_dwordx2 v[70:71], v[60:61], off offset:32 nt
	global_store_dwordx2 v[70:71], v[56:57], off offset:64 nt
	global_store_dwordx2 v[70:71], v[52:53], off offset:96 nt
	s_and_saveexec_b64 s[58:59], s[42:43]
	s_cbranch_execz .LBB0_1136
	v_lshlrev_b64 v[52:53], 6, v[68:69]
	v_lshl_add_u64 v[52:53], s[54:55], 0, v[52:53]
	v_lshlrev_b32_e32 v0, 3, v74
	v_lshl_add_u64 v[52:53], v[52:53], 0, v[0:1]
	global_store_dwordx2 v[52:53], v[2:3], off

.LBB0_1139:
	v_cmp_gt_f32_e32 vcc, s19, v3
	s_mov_b32 s10, 0x3f317217
	v_readlane_b32 s64, v252, 16
	v_cndmask_b32_e64 v68, 0, 32, vcc
	v_ldexp_f32 v68, v3, v68
	v_log_f32_e32 v68, v68
	v_readlane_b32 s66, v252, 18
	v_readlane_b32 s67, v252, 19
	v_readlane_b32 s65, v252, 17
	v_mul_f32_e32 v69, 0x3f317217, v68
	v_fma_f32 v69, v68, s10, -v69
	v_fmac_f32_e32 v69, 0x3377d1cf, v68
	s_mov_b32 s10, 0x7f800000
	v_fmac_f32_e32 v69, 0x3f317217, v68
	v_cmp_lt_f32_e64 s[46:47], |v68|, s10
	s_mov_b32 s10, 0x23c00000
	v_readlane_b32 s68, v252, 20
	v_cndmask_b32_e64 v68, v68, v69, s[46:47]
	v_cndmask_b32_e32 v69, 0, v228, vcc
	v_sub_f32_e32 v68, v68, v69
	v_add_f32_e32 v2, v2, v68
	v_or_b32_e32 v68, s90, v74
	v_mov_b32_e32 v69, v1
	v_lshl_add_u64 v[68:69], v[68:69], 2, s[66:67]
	global_load_dword v68, v[68:69], off
	v_readlane_b32 s69, v252, 21
	v_readlane_b32 s70, v252, 22
	v_readlane_b32 s71, v252, 23
	v_readlane_b32 s72, v252, 24
	v_readlane_b32 s73, v252, 25
	v_readlane_b32 s74, v252, 26
	v_readlane_b32 s75, v252, 27
	v_readlane_b32 s76, v252, 28
	v_readlane_b32 s77, v252, 29
	v_readlane_b32 s78, v252, 30
	v_readlane_b32 s79, v252, 31
	s_waitcnt vmcnt(0)
	v_sub_f32_e32 v2, v68, v2
	v_mul_f32_e32 v2, 0x3fb8aa3b, v2
	v_exp_f32_e32 v2, v2
	s_nop 0
	v_add_f32_e32 v2, 1.0, v2
	s_nop 0
	v_rcp_f32_e32 v2, v2
	s_nop 0
	v_div_scale_f32 v68, s[34:35], v3, v3, v2
	v_rcp_f32_e32 v69, v68
	s_mov_b64 s[34:35], 0x23c00c00
	v_fma_f32 v71, -v68, v69, 1.0
	v_fmac_f32_e32 v69, v71, v69
	v_div_scale_f32 v71, vcc, v2, v3, v2
	v_mul_f32_e32 v74, v71, v69
	v_fma_f32 v75, -v68, v74, v71
	v_fmac_f32_e32 v74, v75, v69
	v_fma_f32 v68, -v68, v74, v71
	v_div_fmas_f32 v68, v68, v69, v74
	v_div_fixup_f32 v68, v68, v3, v2
	v_lshlrev_b64 v[2:3], 12, v[72:73]
	v_mov_b32_e32 v73, v66
	v_mov_b32_e32 v66, v65
	v_mov_b32_e32 v72, v64
	v_pk_mul_f32 v[64:65], v[66:67], v[68:69] op_sel_hi:[1,0]
	v_lshl_add_u64 v[2:3], s[0:1], 0, v[2:3]
	v_pk_mul_f32 v[72:73], v[72:73], v[68:69] op_sel_hi:[1,0]
	v_and_b32_sdwa v69, v64, v225 dst_sel:DWORD dst_unused:UNUSED_PAD src0_sel:WORD_1 src1_sel:DWORD
	v_lshl_add_u64 v[2:3], v[2:3], 0, v[0:1]
	v_mov_b32_e32 v71, v1
	v_and_b32_sdwa v66, v72, v225 dst_sel:DWORD dst_unused:UNUSED_PAD src0_sel:WORD_1 src1_sel:DWORD
	v_add3_u32 v64, v64, v69, s23
	v_lshl_add_u64 v[70:71], v[2:3], 0, v[70:71]
	v_add3_u32 v66, v72, v66, s23
	v_and_b32_e32 v64, 0xffff0000, v64
	v_or_b32_sdwa v64, v64, v66 dst_sel:DWORD dst_unused:UNUSED_PAD src0_sel:DWORD src1_sel:WORD_1
	v_add_co_u32_e32 v66, vcc, s10, v70
	v_cvt_pk_bf16_f32 v65, v73, v65
	s_nop 0
	v_addc_co_u32_e32 v67, vcc, 0, v71, vcc
	global_store_dwordx2 v[66:67], v[64:65], off offset:3072 nt
	v_mov_b32_e32 v64, v60
	v_mov_b32_e32 v65, v62
	v_pk_mul_f32 v[64:65], v[64:65], v[68:69] op_sel_hi:[1,0]
	v_mov_b32_e32 v62, v61
	v_pk_mul_f32 v[60:61], v[62:63], v[68:69] op_sel_hi:[1,0]
	v_and_b32_sdwa v62, v64, v225 dst_sel:DWORD dst_unused:UNUSED_PAD src0_sel:WORD_1 src1_sel:DWORD
	v_add3_u32 v62, v64, v62, s23
	v_and_b32_sdwa v64, v60, v225 dst_sel:DWORD dst_unused:UNUSED_PAD src0_sel:WORD_1 src1_sel:DWORD
	v_add3_u32 v60, v60, v64, s23
	v_and_b32_e32 v60, 0xffff0000, v60
	v_lshl_add_u64 v[2:3], v[70:71], 0, s[34:35]
	v_cvt_pk_bf16_f32 v61, v65, v61
	v_or_b32_sdwa v60, v60, v62 dst_sel:DWORD dst_unused:UNUSED_PAD src0_sel:DWORD src1_sel:WORD_1
	global_store_dwordx2 v[2:3], v[60:61], off offset:32 nt
	v_mov_b32_e32 v60, v56
	v_mov_b32_e32 v61, v58
	v_pk_mul_f32 v[60:61], v[60:61], v[68:69] op_sel_hi:[1,0]
	v_mov_b32_e32 v58, v57
	v_pk_mul_f32 v[56:57], v[58:59], v[68:69] op_sel_hi:[1,0]
	v_and_b32_sdwa v58, v60, v225 dst_sel:DWORD dst_unused:UNUSED_PAD src0_sel:WORD_1 src1_sel:DWORD
	v_add3_u32 v58, v60, v58, s23
	v_and_b32_sdwa v60, v56, v225 dst_sel:DWORD dst_unused:UNUSED_PAD src0_sel:WORD_1 src1_sel:DWORD
	v_add3_u32 v56, v56, v60, s23
	v_and_b32_e32 v56, 0xffff0000, v56
	v_cvt_pk_bf16_f32 v57, v61, v57
	v_or_b32_sdwa v56, v56, v58 dst_sel:DWORD dst_unused:UNUSED_PAD src0_sel:DWORD src1_sel:WORD_1
	global_store_dwordx2 v[2:3], v[56:57], off offset:64 nt
	v_mov_b32_e32 v56, v52
	v_mov_b32_e32 v57, v54
	v_pk_mul_f32 v[56:57], v[56:57], v[68:69] op_sel_hi:[1,0]
	v_mov_b32_e32 v54, v53
	v_pk_mul_f32 v[52:53], v[54:55], v[68:69] op_sel_hi:[1,0]
	v_and_b32_sdwa v54, v56, v225 dst_sel:DWORD dst_unused:UNUSED_PAD src0_sel:WORD_1 src1_sel:DWORD
	v_add3_u32 v54, v56, v54, s23
	v_and_b32_sdwa v56, v52, v225 dst_sel:DWORD dst_unused:UNUSED_PAD src0_sel:WORD_1 src1_sel:DWORD
	v_add3_u32 v52, v52, v56, s23
	v_and_b32_e32 v52, 0xffff0000, v52
	v_cvt_pk_bf16_f32 v53, v57, v53
	v_or_b32_sdwa v52, v52, v54 dst_sel:DWORD dst_unused:UNUSED_PAD src0_sel:DWORD src1_sel:WORD_1
	global_store_dwordx2 v[2:3], v[52:53], off offset:96 nt
	s_or_b64 exec, exec, s[58:59]
	s_xor_b32 s10, s11, 1
	s_and_saveexec_b64 s[46:47], s[44:45]
	s_cbranch_execz .LBB0_1120
.LBB0_1140:
	s_mul_i32 s12, s10, 0x11400
	s_add_i32 s12, s12, 0
	v_add3_u32 v0, s12, v100, v101
	s_waitcnt vmcnt(4)
	v_mov_b64_e32 v[46:47], v[38:39]
	v_mov_b64_e32 v[50:51], v[42:43]
	ds_write_b128 v0, v[24:27]
	ds_write_b128 v0, v[16:19] offset:16
	ds_write_b128 v0, v[28:31] offset:32
	ds_write_b128 v0, v[32:35] offset:48
	v_lshl_add_u32 v0, v102, 1, s12
	v_mov_b64_e32 v[44:45], v[36:37]
	v_mov_b64_e32 v[48:49], v[40:41]
	ds_write_b16 v0, v8 offset:36864
	ds_write_b16_d16_hi v0, v8 offset:37392
	ds_write_b16 v0, v9 offset:37920
	ds_write_b16_d16_hi v0, v9 offset:38448
	ds_write_b16 v0, v10 offset:38976
	ds_write_b16_d16_hi v0, v10 offset:39504
	ds_write_b16 v0, v11 offset:40032
	ds_write_b16_d16_hi v0, v11 offset:40560
	ds_write_b16 v0, v12 offset:41088
	ds_write_b16_d16_hi v0, v12 offset:41616
	ds_write_b16 v0, v13 offset:42144
	ds_write_b16_d16_hi v0, v13 offset:42672
	ds_write_b16 v0, v14 offset:43200
	ds_write_b16_d16_hi v0, v14 offset:43728
	ds_write_b16 v0, v15 offset:44256
	ds_write_b16_d16_hi v0, v15 offset:44784
	ds_write_b16 v0, v20 offset:45312
	ds_write_b16_d16_hi v0, v20 offset:45840
	ds_write_b16 v0, v21 offset:46368
	ds_write_b16_d16_hi v0, v21 offset:46896
	ds_write_b16 v0, v22 offset:47424
	ds_write_b16_d16_hi v0, v22 offset:47952
	ds_write_b16 v0, v23 offset:48480
	ds_write_b16_d16_hi v0, v23 offset:49008
	ds_write_b16 v0, v4 offset:49536
	ds_write_b16_d16_hi v0, v4 offset:50064
	ds_write_b16 v0, v5 offset:50592
	ds_write_b16_d16_hi v0, v5 offset:51120
	ds_write_b16 v0, v6 offset:51648
	ds_write_b16_d16_hi v0, v6 offset:52176
	ds_write_b16 v0, v7 offset:52704
	ds_write_b16_d16_hi v0, v7 offset:53232
	s_branch .LBB0_1120
